# v85 + sgu_item weight-tile staging: 16 row loads issued together instead of 16 serialized load-wait-write steps
# baseline (speedup 1.0000x reference)
.LBB1_871:
	v_lshrrev_b32_e32 v8, 5, v60
	v_lshlrev_b32_e32 v4, 7, v8
	v_mov_b32_e32 v5, 0
	v_lshl_add_u64 v[4:5], v[4:5], 2, v[0:1]
	v_mad_u64_u32 v[6:7], s[6:7], v8, s3, v[2:3]
	v_add_u32_e32 v7, 0x4400, v6
	s_mov_b64 s[6:7], 0x1000
	global_load_dwordx4 v[138:141], v[4:5], off
	v_lshl_add_u64 v[4:5], v[4:5], 0, s[6:7]
	global_load_dwordx4 v[142:145], v[4:5], off
	v_lshl_add_u64 v[4:5], v[4:5], 0, s[6:7]
	global_load_dwordx4 v[146:149], v[4:5], off
	v_lshl_add_u64 v[4:5], v[4:5], 0, s[6:7]
	global_load_dwordx4 v[150:153], v[4:5], off
	v_lshl_add_u64 v[4:5], v[4:5], 0, s[6:7]
	global_load_dwordx4 v[154:157], v[4:5], off
	v_lshl_add_u64 v[4:5], v[4:5], 0, s[6:7]
	global_load_dwordx4 v[158:161], v[4:5], off
	v_lshl_add_u64 v[4:5], v[4:5], 0, s[6:7]
	global_load_dwordx4 v[188:191], v[4:5], off
	v_lshl_add_u64 v[4:5], v[4:5], 0, s[6:7]
	global_load_dwordx4 v[192:195], v[4:5], off
	v_lshl_add_u64 v[4:5], v[4:5], 0, s[6:7]
	global_load_dwordx4 v[196:199], v[4:5], off
	v_lshl_add_u64 v[4:5], v[4:5], 0, s[6:7]
	global_load_dwordx4 v[200:203], v[4:5], off
	v_lshl_add_u64 v[4:5], v[4:5], 0, s[6:7]
	global_load_dwordx4 v[204:207], v[4:5], off
	v_lshl_add_u64 v[4:5], v[4:5], 0, s[6:7]
	global_load_dwordx4 v[208:211], v[4:5], off
	v_lshl_add_u64 v[4:5], v[4:5], 0, s[6:7]
	global_load_dwordx4 v[216:219], v[4:5], off
	v_lshl_add_u64 v[4:5], v[4:5], 0, s[6:7]
	global_load_dwordx4 v[220:223], v[4:5], off
	v_lshl_add_u64 v[4:5], v[4:5], 0, s[6:7]
	global_load_dwordx4 v[224:227], v[4:5], off
	v_lshl_add_u64 v[4:5], v[4:5], 0, s[6:7]
	global_load_dwordx4 v[228:231], v[4:5], off
	s_waitcnt vmcnt(0)
	v_cvt_pk_bf16_f32 v138, v138, v139
	v_cvt_pk_bf16_f32 v139, v140, v141
	s_nop 0
	ds_write_b64 v6, v[138:139] offset:34816
	v_cvt_pk_bf16_f32 v142, v142, v143
	v_cvt_pk_bf16_f32 v143, v144, v145
	s_nop 0
	ds_write_b64 v6, v[142:143] offset:36992
	v_cvt_pk_bf16_f32 v146, v146, v147
	v_cvt_pk_bf16_f32 v147, v148, v149
	s_nop 0
	ds_write_b64 v6, v[146:147] offset:39168
	v_cvt_pk_bf16_f32 v150, v150, v151
	v_cvt_pk_bf16_f32 v151, v152, v153
	s_nop 0
	ds_write_b64 v6, v[150:151] offset:41344
	v_cvt_pk_bf16_f32 v154, v154, v155
	v_cvt_pk_bf16_f32 v155, v156, v157
	s_nop 0
	ds_write_b64 v6, v[154:155] offset:43520
	v_cvt_pk_bf16_f32 v158, v158, v159
	v_cvt_pk_bf16_f32 v159, v160, v161
	s_nop 0
	ds_write_b64 v6, v[158:159] offset:45696
	v_cvt_pk_bf16_f32 v188, v188, v189
	v_cvt_pk_bf16_f32 v189, v190, v191
	s_nop 0
	ds_write_b64 v6, v[188:189] offset:47872
	v_cvt_pk_bf16_f32 v192, v192, v193
	v_cvt_pk_bf16_f32 v193, v194, v195
	s_nop 0
	ds_write_b64 v6, v[192:193] offset:50048
	v_cvt_pk_bf16_f32 v196, v196, v197
	v_cvt_pk_bf16_f32 v197, v198, v199
	s_nop 0
	ds_write_b64 v7, v[196:197] offset:34816
	v_cvt_pk_bf16_f32 v200, v200, v201
	v_cvt_pk_bf16_f32 v201, v202, v203
	s_nop 0
	ds_write_b64 v7, v[200:201] offset:36992
	v_cvt_pk_bf16_f32 v204, v204, v205
	v_cvt_pk_bf16_f32 v205, v206, v207
	s_nop 0
	ds_write_b64 v7, v[204:205] offset:39168
	v_cvt_pk_bf16_f32 v208, v208, v209
	v_cvt_pk_bf16_f32 v209, v210, v211
	s_nop 0
	ds_write_b64 v7, v[208:209] offset:41344
	v_cvt_pk_bf16_f32 v216, v216, v217
	v_cvt_pk_bf16_f32 v217, v218, v219
	s_nop 0
	ds_write_b64 v7, v[216:217] offset:43520
	v_cvt_pk_bf16_f32 v220, v220, v221
	v_cvt_pk_bf16_f32 v221, v222, v223
	s_nop 0
	ds_write_b64 v7, v[220:221] offset:45696
	v_cvt_pk_bf16_f32 v224, v224, v225
	v_cvt_pk_bf16_f32 v225, v226, v227
	s_nop 0
	ds_write_b64 v7, v[224:225] offset:47872
	v_cvt_pk_bf16_f32 v228, v228, v229
	v_cvt_pk_bf16_f32 v229, v230, v231
	s_nop 0
	ds_write_b64 v7, v[228:229] offset:50048
	s_movk_i32 s5, 0x1000
	v_and_b32_e32 v25, 15, v60
	v_and_b32_e32 v0, 48, v60
	v_or_b32_e32 v126, v30, v25
	v_add_u32_e32 v24, 16, v0
	v_mad_u64_u32 v[26:27], s[6:7], v126, s3, v[24:25]
	v_mad_u32_u24 v61, v25, s3, v24
	s_waitcnt lgkmcnt(0)
	s_barrier
	ds_read_b128 v[0:3], v26 offset:34816
	ds_read_b128 v[4:7], v26 offset:34880
	ds_read_b128 v[8:11], v26 offset:34944
	ds_read_b128 v[32:35], v26 offset:35008
	ds_read_b128 v[12:15], v26 offset:39168
	ds_read_b128 v[16:19], v26 offset:39232
	ds_read_b128 v[20:23], v26 offset:39296
	ds_read_b128 v[62:65], v26 offset:39360
	ds_read_b128 v[24:27], v61
	ds_read_b128 v[28:31], v61 offset:4352
	ds_read_b128 v[36:39], v61 offset:8704
	ds_read_b128 v[40:43], v61 offset:13056
	ds_read_b128 v[44:47], v61 offset:17408
	ds_read_b128 v[48:51], v61 offset:21760
	ds_read_b128 v[52:55], v61 offset:26112
	ds_read_b128 v[56:59], v61 offset:30464
	s_setprio 1
	s_waitcnt lgkmcnt(7)
	v_mfma_f32_16x16x32_bf16 v[66:69], v[24:27], v[0:3], 0
	v_mfma_f32_16x16x32_bf16 v[24:27], v[24:27], v[12:15], 0
	s_waitcnt lgkmcnt(6)
	v_mfma_f32_16x16x32_bf16 v[70:73], v[28:31], v[0:3], 0
	v_mfma_f32_16x16x32_bf16 v[28:31], v[28:31], v[12:15], 0
	s_waitcnt lgkmcnt(5)
	v_mfma_f32_16x16x32_bf16 v[74:77], v[36:39], v[0:3], 0
	v_mfma_f32_16x16x32_bf16 v[36:39], v[36:39], v[12:15], 0
	s_waitcnt lgkmcnt(4)
	v_mfma_f32_16x16x32_bf16 v[78:81], v[40:43], v[0:3], 0
	v_mfma_f32_16x16x32_bf16 v[40:43], v[40:43], v[12:15], 0
	s_waitcnt lgkmcnt(3)
	v_mfma_f32_16x16x32_bf16 v[82:85], v[44:47], v[0:3], 0
	v_mfma_f32_16x16x32_bf16 v[44:47], v[44:47], v[12:15], 0
	s_waitcnt lgkmcnt(2)
	v_mfma_f32_16x16x32_bf16 v[86:89], v[48:51], v[0:3], 0
	v_mfma_f32_16x16x32_bf16 v[48:51], v[48:51], v[12:15], 0
	s_waitcnt lgkmcnt(1)
	v_mfma_f32_16x16x32_bf16 v[90:93], v[52:55], v[0:3], 0
	v_mfma_f32_16x16x32_bf16 v[52:55], v[52:55], v[12:15], 0
	s_waitcnt lgkmcnt(0)
	v_mfma_f32_16x16x32_bf16 v[0:3], v[56:59], v[0:3], 0
	v_mfma_f32_16x16x32_bf16 v[12:15], v[56:59], v[12:15], 0
	s_setprio 0
	ds_read_b128 v[56:59], v61 offset:64
	ds_read_b128 v[94:97], v61 offset:4416
	ds_read_b128 v[98:101], v61 offset:8768
	ds_read_b128 v[102:105], v61 offset:13120
	ds_read_b128 v[106:109], v61 offset:17472
	ds_read_b128 v[110:113], v61 offset:21824
	ds_read_b128 v[114:117], v61 offset:26176
	ds_read_b128 v[118:121], v61 offset:30528
	s_setprio 1
	s_waitcnt lgkmcnt(7)
	v_mfma_f32_16x16x32_bf16 v[66:69], v[56:59], v[4:7], v[66:69]
	v_mfma_f32_16x16x32_bf16 v[24:27], v[56:59], v[16:19], v[24:27]
	s_waitcnt lgkmcnt(6)
	v_mfma_f32_16x16x32_bf16 v[56:59], v[94:97], v[4:7], v[70:73]
	v_mfma_f32_16x16x32_bf16 v[28:31], v[94:97], v[16:19], v[28:31]
	s_waitcnt lgkmcnt(5)
	v_mfma_f32_16x16x32_bf16 v[70:73], v[98:101], v[4:7], v[74:77]
	v_mfma_f32_16x16x32_bf16 v[36:39], v[98:101], v[16:19], v[36:39]
	s_waitcnt lgkmcnt(4)
	v_mfma_f32_16x16x32_bf16 v[74:77], v[102:105], v[4:7], v[78:81]
	v_mfma_f32_16x16x32_bf16 v[40:43], v[102:105], v[16:19], v[40:43]
	s_waitcnt lgkmcnt(3)
	v_mfma_f32_16x16x32_bf16 v[78:81], v[106:109], v[4:7], v[82:85]
	v_mfma_f32_16x16x32_bf16 v[44:47], v[106:109], v[16:19], v[44:47]
	s_waitcnt lgkmcnt(2)
	v_mfma_f32_16x16x32_bf16 v[82:85], v[110:113], v[4:7], v[86:89]
	v_mfma_f32_16x16x32_bf16 v[48:51], v[110:113], v[16:19], v[48:51]
	s_waitcnt lgkmcnt(1)
	v_mfma_f32_16x16x32_bf16 v[86:89], v[114:117], v[4:7], v[90:93]
	v_mfma_f32_16x16x32_bf16 v[52:55], v[114:117], v[16:19], v[52:55]
	s_waitcnt lgkmcnt(0)
	v_mfma_f32_16x16x32_bf16 v[0:3], v[118:121], v[4:7], v[0:3]
	v_mfma_f32_16x16x32_bf16 v[4:7], v[118:121], v[16:19], v[12:15]
	s_setprio 0
	s_nop 1
	ds_read_b128 v[12:15], v61 offset:128
	ds_read_b128 v[16:19], v61 offset:4480
	ds_read_b128 v[90:93], v61 offset:8832
	ds_read_b128 v[94:97], v61 offset:13184
	ds_read_b128 v[98:101], v61 offset:17536
	ds_read_b128 v[102:105], v61 offset:21888
	ds_read_b128 v[106:109], v61 offset:26240
	ds_read_b128 v[110:113], v61 offset:30592
	s_setprio 1
	s_waitcnt lgkmcnt(7)
	v_mfma_f32_16x16x32_bf16 v[66:69], v[12:15], v[8:11], v[66:69]
	v_mfma_f32_16x16x32_bf16 v[12:15], v[12:15], v[20:23], v[24:27]
	s_waitcnt lgkmcnt(6)
	v_mfma_f32_16x16x32_bf16 v[24:27], v[16:19], v[8:11], v[56:59]
	v_mfma_f32_16x16x32_bf16 v[16:19], v[16:19], v[20:23], v[28:31]
	s_waitcnt lgkmcnt(5)
	v_mfma_f32_16x16x32_bf16 v[70:73], v[90:93], v[8:11], v[70:73]
	v_mfma_f32_16x16x32_bf16 v[36:39], v[90:93], v[20:23], v[36:39]
	s_waitcnt lgkmcnt(4)
	v_mfma_f32_16x16x32_bf16 v[74:77], v[94:97], v[8:11], v[74:77]
	v_mfma_f32_16x16x32_bf16 v[40:43], v[94:97], v[20:23], v[40:43]
	s_waitcnt lgkmcnt(3)
	v_mfma_f32_16x16x32_bf16 v[78:81], v[98:101], v[8:11], v[78:81]
	v_mfma_f32_16x16x32_bf16 v[90:93], v[98:101], v[20:23], v[44:47]
	s_waitcnt lgkmcnt(2)
	v_mfma_f32_16x16x32_bf16 v[82:85], v[102:105], v[8:11], v[82:85]
	v_mfma_f32_16x16x32_bf16 v[94:97], v[102:105], v[20:23], v[48:51]
	s_waitcnt lgkmcnt(1)
	v_mfma_f32_16x16x32_bf16 v[86:89], v[106:109], v[8:11], v[86:89]
	v_mfma_f32_16x16x32_bf16 v[98:101], v[106:109], v[20:23], v[52:55]
	s_waitcnt lgkmcnt(0)
	v_mfma_f32_16x16x32_bf16 v[0:3], v[110:113], v[8:11], v[0:3]
	v_mfma_f32_16x16x32_bf16 v[102:105], v[110:113], v[20:23], v[4:7]
	s_setprio 0
	s_nop 1
	ds_read_b128 v[4:7], v61 offset:192
	ds_read_b128 v[8:11], v61 offset:4544
	ds_read_b128 v[20:23], v61 offset:8896
	ds_read_b128 v[44:47], v61 offset:13248
	ds_read_b128 v[106:109], v61 offset:17600
	ds_read_b128 v[110:113], v61 offset:21952
	ds_read_b128 v[114:117], v61 offset:26304
	ds_read_b128 v[118:121], v61 offset:30656
	s_setprio 1
	s_waitcnt lgkmcnt(7)
	v_mfma_f32_16x16x32_bf16 v[122:125], v[4:7], v[32:35], v[66:69]
	v_mfma_f32_16x16x32_bf16 v[28:31], v[4:7], v[62:65], v[12:15]
	s_waitcnt lgkmcnt(6)
	v_mfma_f32_16x16x32_bf16 v[56:59], v[8:11], v[32:35], v[24:27]
	v_mfma_f32_16x16x32_bf16 v[24:27], v[8:11], v[62:65], v[16:19]
	s_waitcnt lgkmcnt(5)
	v_mfma_f32_16x16x32_bf16 v[52:55], v[20:23], v[32:35], v[70:73]
	v_mfma_f32_16x16x32_bf16 v[20:23], v[20:23], v[62:65], v[36:39]
	s_waitcnt lgkmcnt(4)
	v_mfma_f32_16x16x32_bf16 v[48:51], v[44:47], v[32:35], v[74:77]
	v_mfma_f32_16x16x32_bf16 v[16:19], v[44:47], v[62:65], v[40:43]
	s_waitcnt lgkmcnt(3)
	v_mfma_f32_16x16x32_bf16 v[44:47], v[106:109], v[32:35], v[78:81]
	v_mfma_f32_16x16x32_bf16 v[12:15], v[106:109], v[62:65], v[90:93]
	s_waitcnt lgkmcnt(2)
	v_mfma_f32_16x16x32_bf16 v[40:43], v[110:113], v[32:35], v[82:85]
	v_mfma_f32_16x16x32_bf16 v[8:11], v[110:113], v[62:65], v[94:97]
	s_waitcnt lgkmcnt(1)
	v_mfma_f32_16x16x32_bf16 v[36:39], v[114:117], v[32:35], v[86:89]
	v_mfma_f32_16x16x32_bf16 v[4:7], v[114:117], v[62:65], v[98:101]
	s_waitcnt lgkmcnt(0)
	v_mfma_f32_16x16x32_bf16 v[32:35], v[118:121], v[32:35], v[0:3]
	v_mfma_f32_16x16x32_bf16 v[0:3], v[118:121], v[62:65], v[102:105]
	s_setprio 0
	v_and_b32_e32 v118, 15, v168
	v_lshrrev_b32_e32 v119, 4, v168
	v_lshrrev_b32_e32 v120, 6, v162
	v_lshl_add_u32 v120, v120, 5, v118
	v_lshlrev_b32_e32 v114, 2, v120
	v_add_u32_e32 v120, s2, v120
	v_lshlrev_b32_e32 v119, 3, v119
	v_lshl_or_b32 v119, s4, 8, v119
	v_lshl_add_u32 v110, v120, 14, v119
	v_lshl_add_u32 v112, v120, 11, v119
	v_add_u32_e32 v120, 16, v120
	v_lshl_add_u32 v111, v120, 14, v119
	v_lshl_add_u32 v113, v120, 11, v119
	v_readlane_b32 s24, v241, 63
	v_readlane_b32 s25, v240, 0
	s_lshl_b64 s[42:43], s[96:97], 9
	s_nop 0
	s_add_u32 s24, s24, s42
	s_addc_u32 s25, s25, s43
	s_add_u32 s46, s76, 0x2000
	s_addc_u32 s47, s77, 0
	s_load_dwordx16 s[4:19], s[0:1], 0x140
	global_load_dword v116, v114, s[24:25]
	global_load_dword v117, v114, s[24:25] offset:64
	global_load_dwordx2 v[66:67], v110, s[46:47] offset:0
	global_load_dwordx2 v[68:69], v110, s[46:47] offset:32
	global_load_dwordx2 v[70:71], v110, s[46:47] offset:64
	global_load_dwordx2 v[72:73], v110, s[46:47] offset:96
	global_load_dwordx2 v[74:75], v110, s[46:47] offset:128
	global_load_dwordx2 v[76:77], v110, s[46:47] offset:160
	global_load_dwordx2 v[78:79], v110, s[46:47] offset:192
	global_load_dwordx2 v[80:81], v110, s[46:47] offset:224
	global_load_dwordx2 v[82:83], v111, s[46:47] offset:0
	global_load_dwordx2 v[84:85], v111, s[46:47] offset:32
	global_load_dwordx2 v[86:87], v111, s[46:47] offset:64
	global_load_dwordx2 v[88:89], v111, s[46:47] offset:96
	global_load_dwordx2 v[90:91], v111, s[46:47] offset:128
	global_load_dwordx2 v[92:93], v111, s[46:47] offset:160
	global_load_dwordx2 v[94:95], v111, s[46:47] offset:192
	global_load_dwordx2 v[96:97], v111, s[46:47] offset:224
	s_mov_b64 s[20:21], s[38:39]
	s_mov_b64 s[22:23], s[40:41]
	s_waitcnt lgkmcnt(0)
	s_waitcnt vmcnt(15)
	v_lshlrev_b32_e32 v98, 16, v66
	v_and_b32_e32 v99, 0xffff0000, v66
	v_lshlrev_b32_e32 v100, 16, v67
	v_and_b32_e32 v101, 0xffff0000, v67
	v_mul_f32_e32 v102, 0x3d372713, v98
	v_mul_f32_e32 v103, 0x3d372713, v99
	v_mul_f32_e32 v104, 0x3d372713, v100
	v_mul_f32_e32 v105, 0x3d372713, v101
	v_mul_f32_e32 v102, v102, v98
	v_mul_f32_e32 v103, v103, v99
	v_mul_f32_e32 v104, v104, v100
	v_mul_f32_e32 v105, v105, v101
	v_fma_f32 v102, v102, v98, v98
	v_fma_f32 v103, v103, v99, v99
	v_fma_f32 v104, v104, v100, v100
	v_fma_f32 v105, v105, v101, v101
	v_mul_f32_e32 v102, 0x3f4c422a, v102
	v_mul_f32_e32 v103, 0x3f4c422a, v103
	v_mul_f32_e32 v104, 0x3f4c422a, v104
	v_mul_f32_e32 v105, 0x3f4c422a, v105
	v_mul_f32_e32 v102, -2.0, v102
	v_mul_f32_e32 v103, -2.0, v103
	v_mul_f32_e32 v104, -2.0, v104
	v_mul_f32_e32 v105, -2.0, v105
	v_mul_f32_e32 v102, 0x3fb8aa3b, v102
	v_mul_f32_e32 v103, 0x3fb8aa3b, v103
	v_mul_f32_e32 v104, 0x3fb8aa3b, v104
	v_mul_f32_e32 v105, 0x3fb8aa3b, v105
	v_exp_f32_e32 v102, v102
	v_exp_f32_e32 v103, v103
	v_exp_f32_e32 v104, v104
	v_exp_f32_e32 v105, v105
	v_add_f32_e32 v102, 1.0, v102
	v_add_f32_e32 v103, 1.0, v103
	v_add_f32_e32 v104, 1.0, v104
	v_add_f32_e32 v105, 1.0, v105
	v_rcp_f32_e32 v102, v102
	v_rcp_f32_e32 v103, v103
	v_rcp_f32_e32 v104, v104
	v_rcp_f32_e32 v105, v105
	v_pk_add_f32 v[106:107], v[122:123], v[116:117] op_sel_hi:[1,0]
	v_pk_add_f32 v[108:109], v[124:125], v[116:117] op_sel_hi:[1,0]
	v_pk_mul_f32 v[98:99], v[102:103], v[98:99]
	v_pk_mul_f32 v[100:101], v[104:105], v[100:101]
	v_pk_mul_f32 v[98:99], v[106:107], v[98:99]
	v_pk_mul_f32 v[100:101], v[108:109], v[100:101]
	s_nop 0
	v_cvt_pk_bf16_f32 v106, v98, v99
	v_cvt_pk_bf16_f32 v107, v100, v101
	global_store_dwordx2 v112, v[106:107], s[12:13] offset:0
	s_waitcnt vmcnt(14)
	v_lshlrev_b32_e32 v98, 16, v68
	v_and_b32_e32 v99, 0xffff0000, v68
	v_lshlrev_b32_e32 v100, 16, v69
	v_and_b32_e32 v101, 0xffff0000, v69
	v_mul_f32_e32 v102, 0x3d372713, v98
	v_mul_f32_e32 v103, 0x3d372713, v99
	v_mul_f32_e32 v104, 0x3d372713, v100
	v_mul_f32_e32 v105, 0x3d372713, v101
	v_mul_f32_e32 v102, v102, v98
	v_mul_f32_e32 v103, v103, v99
	v_mul_f32_e32 v104, v104, v100
	v_mul_f32_e32 v105, v105, v101
	v_fma_f32 v102, v102, v98, v98
	v_fma_f32 v103, v103, v99, v99
	v_fma_f32 v104, v104, v100, v100
	v_fma_f32 v105, v105, v101, v101
	v_mul_f32_e32 v102, 0x3f4c422a, v102
	v_mul_f32_e32 v103, 0x3f4c422a, v103
	v_mul_f32_e32 v104, 0x3f4c422a, v104
	v_mul_f32_e32 v105, 0x3f4c422a, v105
	v_mul_f32_e32 v102, -2.0, v102
	v_mul_f32_e32 v103, -2.0, v103
	v_mul_f32_e32 v104, -2.0, v104
	v_mul_f32_e32 v105, -2.0, v105
	v_mul_f32_e32 v102, 0x3fb8aa3b, v102
	v_mul_f32_e32 v103, 0x3fb8aa3b, v103
	v_mul_f32_e32 v104, 0x3fb8aa3b, v104
	v_mul_f32_e32 v105, 0x3fb8aa3b, v105
	v_exp_f32_e32 v102, v102
	v_exp_f32_e32 v103, v103
	v_exp_f32_e32 v104, v104
	v_exp_f32_e32 v105, v105
	v_add_f32_e32 v102, 1.0, v102
	v_add_f32_e32 v103, 1.0, v103
	v_add_f32_e32 v104, 1.0, v104
	v_add_f32_e32 v105, 1.0, v105
	v_rcp_f32_e32 v102, v102
	v_rcp_f32_e32 v103, v103
	v_rcp_f32_e32 v104, v104
	v_rcp_f32_e32 v105, v105
	v_pk_add_f32 v[106:107], v[56:57], v[116:117] op_sel_hi:[1,0]
	v_pk_add_f32 v[108:109], v[58:59], v[116:117] op_sel_hi:[1,0]
	v_pk_mul_f32 v[98:99], v[102:103], v[98:99]
	v_pk_mul_f32 v[100:101], v[104:105], v[100:101]
	v_pk_mul_f32 v[98:99], v[106:107], v[98:99]
	v_pk_mul_f32 v[100:101], v[108:109], v[100:101]
	s_nop 0
	v_cvt_pk_bf16_f32 v106, v98, v99
	v_cvt_pk_bf16_f32 v107, v100, v101
	global_store_dwordx2 v112, v[106:107], s[12:13] offset:32
	s_waitcnt vmcnt(13)
	v_lshlrev_b32_e32 v98, 16, v70
	v_and_b32_e32 v99, 0xffff0000, v70
	v_lshlrev_b32_e32 v100, 16, v71
	v_and_b32_e32 v101, 0xffff0000, v71
	v_mul_f32_e32 v102, 0x3d372713, v98
	v_mul_f32_e32 v103, 0x3d372713, v99
	v_mul_f32_e32 v104, 0x3d372713, v100
	v_mul_f32_e32 v105, 0x3d372713, v101
	v_mul_f32_e32 v102, v102, v98
	v_mul_f32_e32 v103, v103, v99
	v_mul_f32_e32 v104, v104, v100
	v_mul_f32_e32 v105, v105, v101
	v_fma_f32 v102, v102, v98, v98
	v_fma_f32 v103, v103, v99, v99
	v_fma_f32 v104, v104, v100, v100
	v_fma_f32 v105, v105, v101, v101
	v_mul_f32_e32 v102, 0x3f4c422a, v102
	v_mul_f32_e32 v103, 0x3f4c422a, v103
	v_mul_f32_e32 v104, 0x3f4c422a, v104
	v_mul_f32_e32 v105, 0x3f4c422a, v105
	v_mul_f32_e32 v102, -2.0, v102
	v_mul_f32_e32 v103, -2.0, v103
	v_mul_f32_e32 v104, -2.0, v104
	v_mul_f32_e32 v105, -2.0, v105
	v_mul_f32_e32 v102, 0x3fb8aa3b, v102
	v_mul_f32_e32 v103, 0x3fb8aa3b, v103
	v_mul_f32_e32 v104, 0x3fb8aa3b, v104
	v_mul_f32_e32 v105, 0x3fb8aa3b, v105
	v_exp_f32_e32 v102, v102
	v_exp_f32_e32 v103, v103
	v_exp_f32_e32 v104, v104
	v_exp_f32_e32 v105, v105
	v_add_f32_e32 v102, 1.0, v102
	v_add_f32_e32 v103, 1.0, v103
	v_add_f32_e32 v104, 1.0, v104
	v_add_f32_e32 v105, 1.0, v105
	v_rcp_f32_e32 v102, v102
	v_rcp_f32_e32 v103, v103
	v_rcp_f32_e32 v104, v104
	v_rcp_f32_e32 v105, v105
	v_pk_add_f32 v[106:107], v[52:53], v[116:117] op_sel_hi:[1,0]
	v_pk_add_f32 v[108:109], v[54:55], v[116:117] op_sel_hi:[1,0]
	v_pk_mul_f32 v[98:99], v[102:103], v[98:99]
	v_pk_mul_f32 v[100:101], v[104:105], v[100:101]
	v_pk_mul_f32 v[98:99], v[106:107], v[98:99]
	v_pk_mul_f32 v[100:101], v[108:109], v[100:101]
	s_nop 0
	v_cvt_pk_bf16_f32 v106, v98, v99
	v_cvt_pk_bf16_f32 v107, v100, v101
	global_store_dwordx2 v112, v[106:107], s[12:13] offset:64
	s_waitcnt vmcnt(12)
	v_lshlrev_b32_e32 v98, 16, v72
	v_and_b32_e32 v99, 0xffff0000, v72
	v_lshlrev_b32_e32 v100, 16, v73
	v_and_b32_e32 v101, 0xffff0000, v73
	v_mul_f32_e32 v102, 0x3d372713, v98
	v_mul_f32_e32 v103, 0x3d372713, v99
	v_mul_f32_e32 v104, 0x3d372713, v100
	v_mul_f32_e32 v105, 0x3d372713, v101
	v_mul_f32_e32 v102, v102, v98
	v_mul_f32_e32 v103, v103, v99
	v_mul_f32_e32 v104, v104, v100
	v_mul_f32_e32 v105, v105, v101
	v_fma_f32 v102, v102, v98, v98
	v_fma_f32 v103, v103, v99, v99
	v_fma_f32 v104, v104, v100, v100
	v_fma_f32 v105, v105, v101, v101
	v_mul_f32_e32 v102, 0x3f4c422a, v102
	v_mul_f32_e32 v103, 0x3f4c422a, v103
	v_mul_f32_e32 v104, 0x3f4c422a, v104
	v_mul_f32_e32 v105, 0x3f4c422a, v105
	v_mul_f32_e32 v102, -2.0, v102
	v_mul_f32_e32 v103, -2.0, v103
	v_mul_f32_e32 v104, -2.0, v104
	v_mul_f32_e32 v105, -2.0, v105
	v_mul_f32_e32 v102, 0x3fb8aa3b, v102
	v_mul_f32_e32 v103, 0x3fb8aa3b, v103
	v_mul_f32_e32 v104, 0x3fb8aa3b, v104
	v_mul_f32_e32 v105, 0x3fb8aa3b, v105
	v_exp_f32_e32 v102, v102
	v_exp_f32_e32 v103, v103
	v_exp_f32_e32 v104, v104
	v_exp_f32_e32 v105, v105
	v_add_f32_e32 v102, 1.0, v102
	v_add_f32_e32 v103, 1.0, v103
	v_add_f32_e32 v104, 1.0, v104
	v_add_f32_e32 v105, 1.0, v105
	v_rcp_f32_e32 v102, v102
	v_rcp_f32_e32 v103, v103
	v_rcp_f32_e32 v104, v104
	v_rcp_f32_e32 v105, v105
	v_pk_add_f32 v[106:107], v[48:49], v[116:117] op_sel_hi:[1,0]
	v_pk_add_f32 v[108:109], v[50:51], v[116:117] op_sel_hi:[1,0]
	v_pk_mul_f32 v[98:99], v[102:103], v[98:99]
	v_pk_mul_f32 v[100:101], v[104:105], v[100:101]
	v_pk_mul_f32 v[98:99], v[106:107], v[98:99]
	v_pk_mul_f32 v[100:101], v[108:109], v[100:101]
	s_nop 0
	v_cvt_pk_bf16_f32 v106, v98, v99
	v_cvt_pk_bf16_f32 v107, v100, v101
	global_store_dwordx2 v112, v[106:107], s[12:13] offset:96
	s_waitcnt vmcnt(11)
	v_lshlrev_b32_e32 v98, 16, v74
	v_and_b32_e32 v99, 0xffff0000, v74
	v_lshlrev_b32_e32 v100, 16, v75
	v_and_b32_e32 v101, 0xffff0000, v75
	v_mul_f32_e32 v102, 0x3d372713, v98
	v_mul_f32_e32 v103, 0x3d372713, v99
	v_mul_f32_e32 v104, 0x3d372713, v100
	v_mul_f32_e32 v105, 0x3d372713, v101
	v_mul_f32_e32 v102, v102, v98
	v_mul_f32_e32 v103, v103, v99
	v_mul_f32_e32 v104, v104, v100
	v_mul_f32_e32 v105, v105, v101
	v_fma_f32 v102, v102, v98, v98
	v_fma_f32 v103, v103, v99, v99
	v_fma_f32 v104, v104, v100, v100
	v_fma_f32 v105, v105, v101, v101
	v_mul_f32_e32 v102, 0x3f4c422a, v102
	v_mul_f32_e32 v103, 0x3f4c422a, v103
	v_mul_f32_e32 v104, 0x3f4c422a, v104
	v_mul_f32_e32 v105, 0x3f4c422a, v105
	v_mul_f32_e32 v102, -2.0, v102
	v_mul_f32_e32 v103, -2.0, v103
	v_mul_f32_e32 v104, -2.0, v104
	v_mul_f32_e32 v105, -2.0, v105
	v_mul_f32_e32 v102, 0x3fb8aa3b, v102
	v_mul_f32_e32 v103, 0x3fb8aa3b, v103
	v_mul_f32_e32 v104, 0x3fb8aa3b, v104
	v_mul_f32_e32 v105, 0x3fb8aa3b, v105
	v_exp_f32_e32 v102, v102
	v_exp_f32_e32 v103, v103
	v_exp_f32_e32 v104, v104
	v_exp_f32_e32 v105, v105
	v_add_f32_e32 v102, 1.0, v102
	v_add_f32_e32 v103, 1.0, v103
	v_add_f32_e32 v104, 1.0, v104
	v_add_f32_e32 v105, 1.0, v105
	v_rcp_f32_e32 v102, v102
	v_rcp_f32_e32 v103, v103
	v_rcp_f32_e32 v104, v104
	v_rcp_f32_e32 v105, v105
	v_pk_add_f32 v[106:107], v[44:45], v[116:117] op_sel_hi:[1,0]
	v_pk_add_f32 v[108:109], v[46:47], v[116:117] op_sel_hi:[1,0]
	v_pk_mul_f32 v[98:99], v[102:103], v[98:99]
	v_pk_mul_f32 v[100:101], v[104:105], v[100:101]
	v_pk_mul_f32 v[98:99], v[106:107], v[98:99]
	v_pk_mul_f32 v[100:101], v[108:109], v[100:101]
	s_nop 0
	v_cvt_pk_bf16_f32 v106, v98, v99
	v_cvt_pk_bf16_f32 v107, v100, v101
	global_store_dwordx2 v112, v[106:107], s[12:13] offset:128
	s_waitcnt vmcnt(10)
	v_lshlrev_b32_e32 v98, 16, v76
	v_and_b32_e32 v99, 0xffff0000, v76
	v_lshlrev_b32_e32 v100, 16, v77
	v_and_b32_e32 v101, 0xffff0000, v77
	v_mul_f32_e32 v102, 0x3d372713, v98
	v_mul_f32_e32 v103, 0x3d372713, v99
	v_mul_f32_e32 v104, 0x3d372713, v100
	v_mul_f32_e32 v105, 0x3d372713, v101
	v_mul_f32_e32 v102, v102, v98
	v_mul_f32_e32 v103, v103, v99
	v_mul_f32_e32 v104, v104, v100
	v_mul_f32_e32 v105, v105, v101
	v_fma_f32 v102, v102, v98, v98
	v_fma_f32 v103, v103, v99, v99
	v_fma_f32 v104, v104, v100, v100
	v_fma_f32 v105, v105, v101, v101
	v_mul_f32_e32 v102, 0x3f4c422a, v102
	v_mul_f32_e32 v103, 0x3f4c422a, v103
	v_mul_f32_e32 v104, 0x3f4c422a, v104
	v_mul_f32_e32 v105, 0x3f4c422a, v105
	v_mul_f32_e32 v102, -2.0, v102
	v_mul_f32_e32 v103, -2.0, v103
	v_mul_f32_e32 v104, -2.0, v104
	v_mul_f32_e32 v105, -2.0, v105
	v_mul_f32_e32 v102, 0x3fb8aa3b, v102
	v_mul_f32_e32 v103, 0x3fb8aa3b, v103
	v_mul_f32_e32 v104, 0x3fb8aa3b, v104
	v_mul_f32_e32 v105, 0x3fb8aa3b, v105
	v_exp_f32_e32 v102, v102
	v_exp_f32_e32 v103, v103
	v_exp_f32_e32 v104, v104
	v_exp_f32_e32 v105, v105
	v_add_f32_e32 v102, 1.0, v102
	v_add_f32_e32 v103, 1.0, v103
	v_add_f32_e32 v104, 1.0, v104
	v_add_f32_e32 v105, 1.0, v105
	v_rcp_f32_e32 v102, v102
	v_rcp_f32_e32 v103, v103
	v_rcp_f32_e32 v104, v104
	v_rcp_f32_e32 v105, v105
	v_pk_add_f32 v[106:107], v[40:41], v[116:117] op_sel_hi:[1,0]
	v_pk_add_f32 v[108:109], v[42:43], v[116:117] op_sel_hi:[1,0]
	v_pk_mul_f32 v[98:99], v[102:103], v[98:99]
	v_pk_mul_f32 v[100:101], v[104:105], v[100:101]
	v_pk_mul_f32 v[98:99], v[106:107], v[98:99]
	v_pk_mul_f32 v[100:101], v[108:109], v[100:101]
	s_nop 0
	v_cvt_pk_bf16_f32 v106, v98, v99
	v_cvt_pk_bf16_f32 v107, v100, v101
	global_store_dwordx2 v112, v[106:107], s[12:13] offset:160
	s_waitcnt vmcnt(9)
	v_lshlrev_b32_e32 v98, 16, v78
	v_and_b32_e32 v99, 0xffff0000, v78
	v_lshlrev_b32_e32 v100, 16, v79
	v_and_b32_e32 v101, 0xffff0000, v79
	v_mul_f32_e32 v102, 0x3d372713, v98
	v_mul_f32_e32 v103, 0x3d372713, v99
	v_mul_f32_e32 v104, 0x3d372713, v100
	v_mul_f32_e32 v105, 0x3d372713, v101
	v_mul_f32_e32 v102, v102, v98
	v_mul_f32_e32 v103, v103, v99
	v_mul_f32_e32 v104, v104, v100
	v_mul_f32_e32 v105, v105, v101
	v_fma_f32 v102, v102, v98, v98
	v_fma_f32 v103, v103, v99, v99
	v_fma_f32 v104, v104, v100, v100
	v_fma_f32 v105, v105, v101, v101
	v_mul_f32_e32 v102, 0x3f4c422a, v102
	v_mul_f32_e32 v103, 0x3f4c422a, v103
	v_mul_f32_e32 v104, 0x3f4c422a, v104
	v_mul_f32_e32 v105, 0x3f4c422a, v105
	v_mul_f32_e32 v102, -2.0, v102
	v_mul_f32_e32 v103, -2.0, v103
	v_mul_f32_e32 v104, -2.0, v104
	v_mul_f32_e32 v105, -2.0, v105
	v_mul_f32_e32 v102, 0x3fb8aa3b, v102
	v_mul_f32_e32 v103, 0x3fb8aa3b, v103
	v_mul_f32_e32 v104, 0x3fb8aa3b, v104
	v_mul_f32_e32 v105, 0x3fb8aa3b, v105
	v_exp_f32_e32 v102, v102
	v_exp_f32_e32 v103, v103
	v_exp_f32_e32 v104, v104
	v_exp_f32_e32 v105, v105
	v_add_f32_e32 v102, 1.0, v102
	v_add_f32_e32 v103, 1.0, v103
	v_add_f32_e32 v104, 1.0, v104
	v_add_f32_e32 v105, 1.0, v105
	v_rcp_f32_e32 v102, v102
	v_rcp_f32_e32 v103, v103
	v_rcp_f32_e32 v104, v104
	v_rcp_f32_e32 v105, v105
	v_pk_add_f32 v[106:107], v[36:37], v[116:117] op_sel_hi:[1,0]
	v_pk_add_f32 v[108:109], v[38:39], v[116:117] op_sel_hi:[1,0]
	v_pk_mul_f32 v[98:99], v[102:103], v[98:99]
	v_pk_mul_f32 v[100:101], v[104:105], v[100:101]
	v_pk_mul_f32 v[98:99], v[106:107], v[98:99]
	v_pk_mul_f32 v[100:101], v[108:109], v[100:101]
	s_nop 0
	v_cvt_pk_bf16_f32 v106, v98, v99
	v_cvt_pk_bf16_f32 v107, v100, v101
	global_store_dwordx2 v112, v[106:107], s[12:13] offset:192
	s_waitcnt vmcnt(8)
	v_lshlrev_b32_e32 v98, 16, v80
	v_and_b32_e32 v99, 0xffff0000, v80
	v_lshlrev_b32_e32 v100, 16, v81
	v_and_b32_e32 v101, 0xffff0000, v81
	v_mul_f32_e32 v102, 0x3d372713, v98
	v_mul_f32_e32 v103, 0x3d372713, v99
	v_mul_f32_e32 v104, 0x3d372713, v100
	v_mul_f32_e32 v105, 0x3d372713, v101
	v_mul_f32_e32 v102, v102, v98
	v_mul_f32_e32 v103, v103, v99
	v_mul_f32_e32 v104, v104, v100
	v_mul_f32_e32 v105, v105, v101
	v_fma_f32 v102, v102, v98, v98
	v_fma_f32 v103, v103, v99, v99
	v_fma_f32 v104, v104, v100, v100
	v_fma_f32 v105, v105, v101, v101
	v_mul_f32_e32 v102, 0x3f4c422a, v102
	v_mul_f32_e32 v103, 0x3f4c422a, v103
	v_mul_f32_e32 v104, 0x3f4c422a, v104
	v_mul_f32_e32 v105, 0x3f4c422a, v105
	v_mul_f32_e32 v102, -2.0, v102
	v_mul_f32_e32 v103, -2.0, v103
	v_mul_f32_e32 v104, -2.0, v104
	v_mul_f32_e32 v105, -2.0, v105
	v_mul_f32_e32 v102, 0x3fb8aa3b, v102
	v_mul_f32_e32 v103, 0x3fb8aa3b, v103
	v_mul_f32_e32 v104, 0x3fb8aa3b, v104
	v_mul_f32_e32 v105, 0x3fb8aa3b, v105
	v_exp_f32_e32 v102, v102
	v_exp_f32_e32 v103, v103
	v_exp_f32_e32 v104, v104
	v_exp_f32_e32 v105, v105
	v_add_f32_e32 v102, 1.0, v102
	v_add_f32_e32 v103, 1.0, v103
	v_add_f32_e32 v104, 1.0, v104
	v_add_f32_e32 v105, 1.0, v105
	v_rcp_f32_e32 v102, v102
	v_rcp_f32_e32 v103, v103
	v_rcp_f32_e32 v104, v104
	v_rcp_f32_e32 v105, v105
	v_pk_add_f32 v[106:107], v[32:33], v[116:117] op_sel_hi:[1,0]
	v_pk_add_f32 v[108:109], v[34:35], v[116:117] op_sel_hi:[1,0]
	v_pk_mul_f32 v[98:99], v[102:103], v[98:99]
	v_pk_mul_f32 v[100:101], v[104:105], v[100:101]
	v_pk_mul_f32 v[98:99], v[106:107], v[98:99]
	v_pk_mul_f32 v[100:101], v[108:109], v[100:101]
	s_nop 0
	v_cvt_pk_bf16_f32 v106, v98, v99
	v_cvt_pk_bf16_f32 v107, v100, v101
	global_store_dwordx2 v112, v[106:107], s[12:13] offset:224
	s_waitcnt vmcnt(7)
	v_lshlrev_b32_e32 v98, 16, v82
	v_and_b32_e32 v99, 0xffff0000, v82
	v_lshlrev_b32_e32 v100, 16, v83
	v_and_b32_e32 v101, 0xffff0000, v83
	v_mul_f32_e32 v102, 0x3d372713, v98
	v_mul_f32_e32 v103, 0x3d372713, v99
	v_mul_f32_e32 v104, 0x3d372713, v100
	v_mul_f32_e32 v105, 0x3d372713, v101
	v_mul_f32_e32 v102, v102, v98
	v_mul_f32_e32 v103, v103, v99
	v_mul_f32_e32 v104, v104, v100
	v_mul_f32_e32 v105, v105, v101
	v_fma_f32 v102, v102, v98, v98
	v_fma_f32 v103, v103, v99, v99
	v_fma_f32 v104, v104, v100, v100
	v_fma_f32 v105, v105, v101, v101
	v_mul_f32_e32 v102, 0x3f4c422a, v102
	v_mul_f32_e32 v103, 0x3f4c422a, v103
	v_mul_f32_e32 v104, 0x3f4c422a, v104
	v_mul_f32_e32 v105, 0x3f4c422a, v105
	v_mul_f32_e32 v102, -2.0, v102
	v_mul_f32_e32 v103, -2.0, v103
	v_mul_f32_e32 v104, -2.0, v104
	v_mul_f32_e32 v105, -2.0, v105
	v_mul_f32_e32 v102, 0x3fb8aa3b, v102
	v_mul_f32_e32 v103, 0x3fb8aa3b, v103
	v_mul_f32_e32 v104, 0x3fb8aa3b, v104
	v_mul_f32_e32 v105, 0x3fb8aa3b, v105
	v_exp_f32_e32 v102, v102
	v_exp_f32_e32 v103, v103
	v_exp_f32_e32 v104, v104
	v_exp_f32_e32 v105, v105
	v_add_f32_e32 v102, 1.0, v102
	v_add_f32_e32 v103, 1.0, v103
	v_add_f32_e32 v104, 1.0, v104
	v_add_f32_e32 v105, 1.0, v105
	v_rcp_f32_e32 v102, v102
	v_rcp_f32_e32 v103, v103
	v_rcp_f32_e32 v104, v104
	v_rcp_f32_e32 v105, v105
	v_pk_add_f32 v[106:107], v[28:29], v[116:117] op_sel:[0,1] op_sel_hi:[1,1]
	v_pk_add_f32 v[108:109], v[30:31], v[116:117] op_sel:[0,1] op_sel_hi:[1,1]
	v_pk_mul_f32 v[98:99], v[102:103], v[98:99]
	v_pk_mul_f32 v[100:101], v[104:105], v[100:101]
	v_pk_mul_f32 v[98:99], v[106:107], v[98:99]
	v_pk_mul_f32 v[100:101], v[108:109], v[100:101]
	s_nop 0
	v_cvt_pk_bf16_f32 v106, v98, v99
	v_cvt_pk_bf16_f32 v107, v100, v101
	global_store_dwordx2 v113, v[106:107], s[12:13] offset:0
	s_waitcnt vmcnt(6)
	v_lshlrev_b32_e32 v98, 16, v84
	v_and_b32_e32 v99, 0xffff0000, v84
	v_lshlrev_b32_e32 v100, 16, v85
	v_and_b32_e32 v101, 0xffff0000, v85
	v_mul_f32_e32 v102, 0x3d372713, v98
	v_mul_f32_e32 v103, 0x3d372713, v99
	v_mul_f32_e32 v104, 0x3d372713, v100
	v_mul_f32_e32 v105, 0x3d372713, v101
	v_mul_f32_e32 v102, v102, v98
	v_mul_f32_e32 v103, v103, v99
	v_mul_f32_e32 v104, v104, v100
	v_mul_f32_e32 v105, v105, v101
	v_fma_f32 v102, v102, v98, v98
	v_fma_f32 v103, v103, v99, v99
	v_fma_f32 v104, v104, v100, v100
	v_fma_f32 v105, v105, v101, v101
	v_mul_f32_e32 v102, 0x3f4c422a, v102
	v_mul_f32_e32 v103, 0x3f4c422a, v103
	v_mul_f32_e32 v104, 0x3f4c422a, v104
	v_mul_f32_e32 v105, 0x3f4c422a, v105
	v_mul_f32_e32 v102, -2.0, v102
	v_mul_f32_e32 v103, -2.0, v103
	v_mul_f32_e32 v104, -2.0, v104
	v_mul_f32_e32 v105, -2.0, v105
	v_mul_f32_e32 v102, 0x3fb8aa3b, v102
	v_mul_f32_e32 v103, 0x3fb8aa3b, v103
	v_mul_f32_e32 v104, 0x3fb8aa3b, v104
	v_mul_f32_e32 v105, 0x3fb8aa3b, v105
	v_exp_f32_e32 v102, v102
	v_exp_f32_e32 v103, v103
	v_exp_f32_e32 v104, v104
	v_exp_f32_e32 v105, v105
	v_add_f32_e32 v102, 1.0, v102
	v_add_f32_e32 v103, 1.0, v103
	v_add_f32_e32 v104, 1.0, v104
	v_add_f32_e32 v105, 1.0, v105
	v_rcp_f32_e32 v102, v102
	v_rcp_f32_e32 v103, v103
	v_rcp_f32_e32 v104, v104
	v_rcp_f32_e32 v105, v105
	v_pk_add_f32 v[106:107], v[24:25], v[116:117] op_sel:[0,1] op_sel_hi:[1,1]
	v_pk_add_f32 v[108:109], v[26:27], v[116:117] op_sel:[0,1] op_sel_hi:[1,1]
	v_pk_mul_f32 v[98:99], v[102:103], v[98:99]
	v_pk_mul_f32 v[100:101], v[104:105], v[100:101]
	v_pk_mul_f32 v[98:99], v[106:107], v[98:99]
	v_pk_mul_f32 v[100:101], v[108:109], v[100:101]
	s_nop 0
	v_cvt_pk_bf16_f32 v106, v98, v99
	v_cvt_pk_bf16_f32 v107, v100, v101
	global_store_dwordx2 v113, v[106:107], s[12:13] offset:32
	s_waitcnt vmcnt(5)
	v_lshlrev_b32_e32 v98, 16, v86
	v_and_b32_e32 v99, 0xffff0000, v86
	v_lshlrev_b32_e32 v100, 16, v87
	v_and_b32_e32 v101, 0xffff0000, v87
	v_mul_f32_e32 v102, 0x3d372713, v98
	v_mul_f32_e32 v103, 0x3d372713, v99
	v_mul_f32_e32 v104, 0x3d372713, v100
	v_mul_f32_e32 v105, 0x3d372713, v101
	v_mul_f32_e32 v102, v102, v98
	v_mul_f32_e32 v103, v103, v99
	v_mul_f32_e32 v104, v104, v100
	v_mul_f32_e32 v105, v105, v101
	v_fma_f32 v102, v102, v98, v98
	v_fma_f32 v103, v103, v99, v99
	v_fma_f32 v104, v104, v100, v100
	v_fma_f32 v105, v105, v101, v101
	v_mul_f32_e32 v102, 0x3f4c422a, v102
	v_mul_f32_e32 v103, 0x3f4c422a, v103
	v_mul_f32_e32 v104, 0x3f4c422a, v104
	v_mul_f32_e32 v105, 0x3f4c422a, v105
	v_mul_f32_e32 v102, -2.0, v102
	v_mul_f32_e32 v103, -2.0, v103
	v_mul_f32_e32 v104, -2.0, v104
	v_mul_f32_e32 v105, -2.0, v105
	v_mul_f32_e32 v102, 0x3fb8aa3b, v102
	v_mul_f32_e32 v103, 0x3fb8aa3b, v103
	v_mul_f32_e32 v104, 0x3fb8aa3b, v104
	v_mul_f32_e32 v105, 0x3fb8aa3b, v105
	v_exp_f32_e32 v102, v102
	v_exp_f32_e32 v103, v103
	v_exp_f32_e32 v104, v104
	v_exp_f32_e32 v105, v105
	v_add_f32_e32 v102, 1.0, v102
	v_add_f32_e32 v103, 1.0, v103
	v_add_f32_e32 v104, 1.0, v104
	v_add_f32_e32 v105, 1.0, v105
	v_rcp_f32_e32 v102, v102
	v_rcp_f32_e32 v103, v103
	v_rcp_f32_e32 v104, v104
	v_rcp_f32_e32 v105, v105
	v_pk_add_f32 v[106:107], v[20:21], v[116:117] op_sel:[0,1] op_sel_hi:[1,1]
	v_pk_add_f32 v[108:109], v[22:23], v[116:117] op_sel:[0,1] op_sel_hi:[1,1]
	v_pk_mul_f32 v[98:99], v[102:103], v[98:99]
	v_pk_mul_f32 v[100:101], v[104:105], v[100:101]
	v_pk_mul_f32 v[98:99], v[106:107], v[98:99]
	v_pk_mul_f32 v[100:101], v[108:109], v[100:101]
	s_nop 0
	v_cvt_pk_bf16_f32 v106, v98, v99
	v_cvt_pk_bf16_f32 v107, v100, v101
	global_store_dwordx2 v113, v[106:107], s[12:13] offset:64
	s_waitcnt vmcnt(4)
	v_lshlrev_b32_e32 v98, 16, v88
	v_and_b32_e32 v99, 0xffff0000, v88
	v_lshlrev_b32_e32 v100, 16, v89
	v_and_b32_e32 v101, 0xffff0000, v89
	v_mul_f32_e32 v102, 0x3d372713, v98
	v_mul_f32_e32 v103, 0x3d372713, v99
	v_mul_f32_e32 v104, 0x3d372713, v100
	v_mul_f32_e32 v105, 0x3d372713, v101
	v_mul_f32_e32 v102, v102, v98
	v_mul_f32_e32 v103, v103, v99
	v_mul_f32_e32 v104, v104, v100
	v_mul_f32_e32 v105, v105, v101
	v_fma_f32 v102, v102, v98, v98
	v_fma_f32 v103, v103, v99, v99
	v_fma_f32 v104, v104, v100, v100
	v_fma_f32 v105, v105, v101, v101
	v_mul_f32_e32 v102, 0x3f4c422a, v102
	v_mul_f32_e32 v103, 0x3f4c422a, v103
	v_mul_f32_e32 v104, 0x3f4c422a, v104
	v_mul_f32_e32 v105, 0x3f4c422a, v105
	v_mul_f32_e32 v102, -2.0, v102
	v_mul_f32_e32 v103, -2.0, v103
	v_mul_f32_e32 v104, -2.0, v104
	v_mul_f32_e32 v105, -2.0, v105
	v_mul_f32_e32 v102, 0x3fb8aa3b, v102
	v_mul_f32_e32 v103, 0x3fb8aa3b, v103
	v_mul_f32_e32 v104, 0x3fb8aa3b, v104
	v_mul_f32_e32 v105, 0x3fb8aa3b, v105
	v_exp_f32_e32 v102, v102
	v_exp_f32_e32 v103, v103
	v_exp_f32_e32 v104, v104
	v_exp_f32_e32 v105, v105
	v_add_f32_e32 v102, 1.0, v102
	v_add_f32_e32 v103, 1.0, v103
	v_add_f32_e32 v104, 1.0, v104
	v_add_f32_e32 v105, 1.0, v105
	v_rcp_f32_e32 v102, v102
	v_rcp_f32_e32 v103, v103
	v_rcp_f32_e32 v104, v104
	v_rcp_f32_e32 v105, v105
	v_pk_add_f32 v[106:107], v[16:17], v[116:117] op_sel:[0,1] op_sel_hi:[1,1]
	v_pk_add_f32 v[108:109], v[18:19], v[116:117] op_sel:[0,1] op_sel_hi:[1,1]
	v_pk_mul_f32 v[98:99], v[102:103], v[98:99]
	v_pk_mul_f32 v[100:101], v[104:105], v[100:101]
	v_pk_mul_f32 v[98:99], v[106:107], v[98:99]
	v_pk_mul_f32 v[100:101], v[108:109], v[100:101]
	s_nop 0
	v_cvt_pk_bf16_f32 v106, v98, v99
	v_cvt_pk_bf16_f32 v107, v100, v101
	global_store_dwordx2 v113, v[106:107], s[12:13] offset:96
	s_waitcnt vmcnt(3)
	v_lshlrev_b32_e32 v98, 16, v90
	v_and_b32_e32 v99, 0xffff0000, v90
	v_lshlrev_b32_e32 v100, 16, v91
	v_and_b32_e32 v101, 0xffff0000, v91
	v_mul_f32_e32 v102, 0x3d372713, v98
	v_mul_f32_e32 v103, 0x3d372713, v99
	v_mul_f32_e32 v104, 0x3d372713, v100
	v_mul_f32_e32 v105, 0x3d372713, v101
	v_mul_f32_e32 v102, v102, v98
	v_mul_f32_e32 v103, v103, v99
	v_mul_f32_e32 v104, v104, v100
	v_mul_f32_e32 v105, v105, v101
	v_fma_f32 v102, v102, v98, v98
	v_fma_f32 v103, v103, v99, v99
	v_fma_f32 v104, v104, v100, v100
	v_fma_f32 v105, v105, v101, v101
	v_mul_f32_e32 v102, 0x3f4c422a, v102
	v_mul_f32_e32 v103, 0x3f4c422a, v103
	v_mul_f32_e32 v104, 0x3f4c422a, v104
	v_mul_f32_e32 v105, 0x3f4c422a, v105
	v_mul_f32_e32 v102, -2.0, v102
	v_mul_f32_e32 v103, -2.0, v103
	v_mul_f32_e32 v104, -2.0, v104
	v_mul_f32_e32 v105, -2.0, v105
	v_mul_f32_e32 v102, 0x3fb8aa3b, v102
	v_mul_f32_e32 v103, 0x3fb8aa3b, v103
	v_mul_f32_e32 v104, 0x3fb8aa3b, v104
	v_mul_f32_e32 v105, 0x3fb8aa3b, v105
	v_exp_f32_e32 v102, v102
	v_exp_f32_e32 v103, v103
	v_exp_f32_e32 v104, v104
	v_exp_f32_e32 v105, v105
	v_add_f32_e32 v102, 1.0, v102
	v_add_f32_e32 v103, 1.0, v103
	v_add_f32_e32 v104, 1.0, v104
	v_add_f32_e32 v105, 1.0, v105
	v_rcp_f32_e32 v102, v102
	v_rcp_f32_e32 v103, v103
	v_rcp_f32_e32 v104, v104
	v_rcp_f32_e32 v105, v105
	v_pk_add_f32 v[106:107], v[12:13], v[116:117] op_sel:[0,1] op_sel_hi:[1,1]
	v_pk_add_f32 v[108:109], v[14:15], v[116:117] op_sel:[0,1] op_sel_hi:[1,1]
	v_pk_mul_f32 v[98:99], v[102:103], v[98:99]
	v_pk_mul_f32 v[100:101], v[104:105], v[100:101]
	v_pk_mul_f32 v[98:99], v[106:107], v[98:99]
	v_pk_mul_f32 v[100:101], v[108:109], v[100:101]
	s_nop 0
	v_cvt_pk_bf16_f32 v106, v98, v99
	v_cvt_pk_bf16_f32 v107, v100, v101
	global_store_dwordx2 v113, v[106:107], s[12:13] offset:128
	s_waitcnt vmcnt(2)
	v_lshlrev_b32_e32 v98, 16, v92
	v_and_b32_e32 v99, 0xffff0000, v92
	v_lshlrev_b32_e32 v100, 16, v93
	v_and_b32_e32 v101, 0xffff0000, v93
	v_mul_f32_e32 v102, 0x3d372713, v98
	v_mul_f32_e32 v103, 0x3d372713, v99
	v_mul_f32_e32 v104, 0x3d372713, v100
	v_mul_f32_e32 v105, 0x3d372713, v101
	v_mul_f32_e32 v102, v102, v98
	v_mul_f32_e32 v103, v103, v99
	v_mul_f32_e32 v104, v104, v100
	v_mul_f32_e32 v105, v105, v101
	v_fma_f32 v102, v102, v98, v98
	v_fma_f32 v103, v103, v99, v99
	v_fma_f32 v104, v104, v100, v100
	v_fma_f32 v105, v105, v101, v101
	v_mul_f32_e32 v102, 0x3f4c422a, v102
	v_mul_f32_e32 v103, 0x3f4c422a, v103
	v_mul_f32_e32 v104, 0x3f4c422a, v104
	v_mul_f32_e32 v105, 0x3f4c422a, v105
	v_mul_f32_e32 v102, -2.0, v102
	v_mul_f32_e32 v103, -2.0, v103
	v_mul_f32_e32 v104, -2.0, v104
	v_mul_f32_e32 v105, -2.0, v105
	v_mul_f32_e32 v102, 0x3fb8aa3b, v102
	v_mul_f32_e32 v103, 0x3fb8aa3b, v103
	v_mul_f32_e32 v104, 0x3fb8aa3b, v104
	v_mul_f32_e32 v105, 0x3fb8aa3b, v105
	v_exp_f32_e32 v102, v102
	v_exp_f32_e32 v103, v103
	v_exp_f32_e32 v104, v104
	v_exp_f32_e32 v105, v105
	v_add_f32_e32 v102, 1.0, v102
	v_add_f32_e32 v103, 1.0, v103
	v_add_f32_e32 v104, 1.0, v104
	v_add_f32_e32 v105, 1.0, v105
	v_rcp_f32_e32 v102, v102
	v_rcp_f32_e32 v103, v103
	v_rcp_f32_e32 v104, v104
	v_rcp_f32_e32 v105, v105
	v_pk_add_f32 v[106:107], v[8:9], v[116:117] op_sel:[0,1] op_sel_hi:[1,1]
	v_pk_add_f32 v[108:109], v[10:11], v[116:117] op_sel:[0,1] op_sel_hi:[1,1]
	v_pk_mul_f32 v[98:99], v[102:103], v[98:99]
	v_pk_mul_f32 v[100:101], v[104:105], v[100:101]
	v_pk_mul_f32 v[98:99], v[106:107], v[98:99]
	v_pk_mul_f32 v[100:101], v[108:109], v[100:101]
	s_nop 0
	v_cvt_pk_bf16_f32 v106, v98, v99
	v_cvt_pk_bf16_f32 v107, v100, v101
	global_store_dwordx2 v113, v[106:107], s[12:13] offset:160
	s_waitcnt vmcnt(1)
	v_lshlrev_b32_e32 v98, 16, v94
	v_and_b32_e32 v99, 0xffff0000, v94
	v_lshlrev_b32_e32 v100, 16, v95
	v_and_b32_e32 v101, 0xffff0000, v95
	v_mul_f32_e32 v102, 0x3d372713, v98
	v_mul_f32_e32 v103, 0x3d372713, v99
	v_mul_f32_e32 v104, 0x3d372713, v100
	v_mul_f32_e32 v105, 0x3d372713, v101
	v_mul_f32_e32 v102, v102, v98
	v_mul_f32_e32 v103, v103, v99
	v_mul_f32_e32 v104, v104, v100
	v_mul_f32_e32 v105, v105, v101
	v_fma_f32 v102, v102, v98, v98
	v_fma_f32 v103, v103, v99, v99
	v_fma_f32 v104, v104, v100, v100
	v_fma_f32 v105, v105, v101, v101
	v_mul_f32_e32 v102, 0x3f4c422a, v102
	v_mul_f32_e32 v103, 0x3f4c422a, v103
	v_mul_f32_e32 v104, 0x3f4c422a, v104
	v_mul_f32_e32 v105, 0x3f4c422a, v105
	v_mul_f32_e32 v102, -2.0, v102
	v_mul_f32_e32 v103, -2.0, v103
	v_mul_f32_e32 v104, -2.0, v104
	v_mul_f32_e32 v105, -2.0, v105
	v_mul_f32_e32 v102, 0x3fb8aa3b, v102
	v_mul_f32_e32 v103, 0x3fb8aa3b, v103
	v_mul_f32_e32 v104, 0x3fb8aa3b, v104
	v_mul_f32_e32 v105, 0x3fb8aa3b, v105
	v_exp_f32_e32 v102, v102
	v_exp_f32_e32 v103, v103
	v_exp_f32_e32 v104, v104
	v_exp_f32_e32 v105, v105
	v_add_f32_e32 v102, 1.0, v102
	v_add_f32_e32 v103, 1.0, v103
	v_add_f32_e32 v104, 1.0, v104
	v_add_f32_e32 v105, 1.0, v105
	v_rcp_f32_e32 v102, v102
	v_rcp_f32_e32 v103, v103
	v_rcp_f32_e32 v104, v104
	v_rcp_f32_e32 v105, v105
	v_pk_add_f32 v[106:107], v[4:5], v[116:117] op_sel:[0,1] op_sel_hi:[1,1]
	v_pk_add_f32 v[108:109], v[6:7], v[116:117] op_sel:[0,1] op_sel_hi:[1,1]
	v_pk_mul_f32 v[98:99], v[102:103], v[98:99]
	v_pk_mul_f32 v[100:101], v[104:105], v[100:101]
	v_pk_mul_f32 v[98:99], v[106:107], v[98:99]
	v_pk_mul_f32 v[100:101], v[108:109], v[100:101]
	s_nop 0
	v_cvt_pk_bf16_f32 v106, v98, v99
	v_cvt_pk_bf16_f32 v107, v100, v101
	global_store_dwordx2 v113, v[106:107], s[12:13] offset:192
	s_waitcnt vmcnt(0)
	v_lshlrev_b32_e32 v98, 16, v96
	v_and_b32_e32 v99, 0xffff0000, v96
	v_lshlrev_b32_e32 v100, 16, v97
	v_and_b32_e32 v101, 0xffff0000, v97
	v_mul_f32_e32 v102, 0x3d372713, v98
	v_mul_f32_e32 v103, 0x3d372713, v99
	v_mul_f32_e32 v104, 0x3d372713, v100
	v_mul_f32_e32 v105, 0x3d372713, v101
	v_mul_f32_e32 v102, v102, v98
	v_mul_f32_e32 v103, v103, v99
	v_mul_f32_e32 v104, v104, v100
	v_mul_f32_e32 v105, v105, v101
	v_fma_f32 v102, v102, v98, v98
	v_fma_f32 v103, v103, v99, v99
	v_fma_f32 v104, v104, v100, v100
	v_fma_f32 v105, v105, v101, v101
	v_mul_f32_e32 v102, 0x3f4c422a, v102
	v_mul_f32_e32 v103, 0x3f4c422a, v103
	v_mul_f32_e32 v104, 0x3f4c422a, v104
	v_mul_f32_e32 v105, 0x3f4c422a, v105
	v_mul_f32_e32 v102, -2.0, v102
	v_mul_f32_e32 v103, -2.0, v103
	v_mul_f32_e32 v104, -2.0, v104
	v_mul_f32_e32 v105, -2.0, v105
	v_mul_f32_e32 v102, 0x3fb8aa3b, v102
	v_mul_f32_e32 v103, 0x3fb8aa3b, v103
	v_mul_f32_e32 v104, 0x3fb8aa3b, v104
	v_mul_f32_e32 v105, 0x3fb8aa3b, v105
	v_exp_f32_e32 v102, v102
	v_exp_f32_e32 v103, v103
	v_exp_f32_e32 v104, v104
	v_exp_f32_e32 v105, v105
	v_add_f32_e32 v102, 1.0, v102
	v_add_f32_e32 v103, 1.0, v103
	v_add_f32_e32 v104, 1.0, v104
	v_add_f32_e32 v105, 1.0, v105
	v_rcp_f32_e32 v102, v102
	v_rcp_f32_e32 v103, v103
	v_rcp_f32_e32 v104, v104
	v_rcp_f32_e32 v105, v105
	v_pk_add_f32 v[106:107], v[0:1], v[116:117] op_sel:[0,1] op_sel_hi:[1,1]
	v_pk_add_f32 v[108:109], v[2:3], v[116:117] op_sel:[0,1] op_sel_hi:[1,1]
	v_pk_mul_f32 v[98:99], v[102:103], v[98:99]
	v_pk_mul_f32 v[100:101], v[104:105], v[100:101]
	v_pk_mul_f32 v[98:99], v[106:107], v[98:99]
	v_pk_mul_f32 v[100:101], v[108:109], v[100:101]
	s_nop 0
	v_cvt_pk_bf16_f32 v106, v98, v99
	v_cvt_pk_bf16_f32 v107, v100, v101
	global_store_dwordx2 v113, v[106:107], s[12:13] offset:224
	s_mov_b64 s[30:31], 0
